# loop-edge: FFN-up K-loops' counter/next-address SALU moved from the load-segment head to the MFMA-segment tail (before the last barrier)
# speedup vs baseline: 1.0064x; 1.0064x over previous
.LBB0_110:
	s_ashr_i32 s19, s18, 31
	s_lshl_b64 s[20:21], s[18:19], 19
	s_add_u32 s20, s38, s20
	s_addc_u32 s21, s39, s21
	s_and_b64 s[22:23], s[2:3], exec
	s_cselect_b32 s19, s21, s27
	s_cselect_b32 s52, s20, s26
	s_ashr_i32 s17, s16, 31
	s_lshl_b64 s[22:23], s[16:17], 19
	s_add_u32 s22, s40, s22
	s_addc_u32 s23, s41, s23
	s_and_b64 s[30:31], s[2:3], exec
	s_cselect_b32 s17, s23, s29
	s_cselect_b32 s53, s22, s28
	s_add_u32 s26, s26, 0x40080
	s_addc_u32 s27, s27, 0
	s_add_u32 s54, s28, 0x100
	v_mov_b32_e32 v2, 0
	s_addc_u32 s55, s29, 0
	s_mov_b32 s56, -2
	v_mov_b32_e32 v3, v2
	v_mov_b32_e32 v4, v2
	v_mov_b32_e32 v5, v2
	v_mov_b32_e32 v6, v2
	v_mov_b32_e32 v7, v2
	v_mov_b32_e32 v8, v2
	v_mov_b32_e32 v9, v2
	v_mov_b32_e32 v18, v2
	v_mov_b32_e32 v19, v2
	v_mov_b32_e32 v20, v2
	v_mov_b32_e32 v21, v2
	v_mov_b32_e32 v22, v2
	v_mov_b32_e32 v23, v2
	v_mov_b32_e32 v24, v2
	v_mov_b32_e32 v25, v2
	v_mov_b32_e32 v34, v2
	v_mov_b32_e32 v35, v2
	v_mov_b32_e32 v36, v2
	v_mov_b32_e32 v37, v2
	v_mov_b32_e32 v38, v2
	v_mov_b32_e32 v39, v2
	v_mov_b32_e32 v40, v2
	v_mov_b32_e32 v41, v2
	v_mov_b32_e32 v50, v2
	v_mov_b32_e32 v51, v2
	v_mov_b32_e32 v52, v2
	v_mov_b32_e32 v53, v2
	v_mov_b32_e32 v54, v2
	v_mov_b32_e32 v55, v2
	v_mov_b32_e32 v56, v2
	v_mov_b32_e32 v57, v2
	v_mov_b32_e32 v10, v2
	v_mov_b32_e32 v11, v2
	v_mov_b32_e32 v12, v2
	v_mov_b32_e32 v13, v2
	v_mov_b32_e32 v14, v2
	v_mov_b32_e32 v15, v2
	v_mov_b32_e32 v16, v2
	v_mov_b32_e32 v17, v2
	v_mov_b32_e32 v26, v2
	v_mov_b32_e32 v27, v2
	v_mov_b32_e32 v28, v2
	v_mov_b32_e32 v29, v2
	v_mov_b32_e32 v30, v2
	v_mov_b32_e32 v31, v2
	v_mov_b32_e32 v32, v2
	v_mov_b32_e32 v33, v2
	v_mov_b32_e32 v42, v2
	v_mov_b32_e32 v43, v2
	v_mov_b32_e32 v44, v2
	v_mov_b32_e32 v45, v2
	v_mov_b32_e32 v46, v2
	v_mov_b32_e32 v47, v2
	v_mov_b32_e32 v48, v2
	v_mov_b32_e32 v49, v2
	v_mov_b32_e32 v58, v2
	v_mov_b32_e32 v59, v2
	v_mov_b32_e32 v60, v2
	v_mov_b32_e32 v61, v2
	v_mov_b32_e32 v62, v2
	v_mov_b32_e32 v63, v2
	v_mov_b32_e32 v64, v2
	v_mov_b32_e32 v65, v2
	v_mov_b32_e32 v66, v2
	v_mov_b32_e32 v67, v2
	v_mov_b32_e32 v68, v2
	v_mov_b32_e32 v69, v2
	v_mov_b32_e32 v70, v2
	v_mov_b32_e32 v71, v2
	v_mov_b32_e32 v72, v2
	v_mov_b32_e32 v73, v2
	v_mov_b32_e32 v82, v2
	v_mov_b32_e32 v83, v2
	v_mov_b32_e32 v84, v2
	v_mov_b32_e32 v85, v2
	v_mov_b32_e32 v86, v2
	v_mov_b32_e32 v87, v2
	v_mov_b32_e32 v88, v2
	v_mov_b32_e32 v89, v2
	v_mov_b32_e32 v98, v2
	v_mov_b32_e32 v99, v2
	v_mov_b32_e32 v100, v2
	v_mov_b32_e32 v101, v2
	v_mov_b32_e32 v102, v2
	v_mov_b32_e32 v103, v2
	v_mov_b32_e32 v104, v2
	v_mov_b32_e32 v105, v2
	v_mov_b32_e32 v114, v2
	v_mov_b32_e32 v115, v2
	v_mov_b32_e32 v116, v2
	v_mov_b32_e32 v117, v2
	v_mov_b32_e32 v118, v2
	v_mov_b32_e32 v119, v2
	v_mov_b32_e32 v120, v2
	v_mov_b32_e32 v121, v2
	v_mov_b32_e32 v74, v2
	v_mov_b32_e32 v75, v2
	v_mov_b32_e32 v76, v2
	v_mov_b32_e32 v77, v2
	v_mov_b32_e32 v78, v2
	v_mov_b32_e32 v79, v2
	v_mov_b32_e32 v80, v2
	v_mov_b32_e32 v81, v2
	v_mov_b32_e32 v90, v2
	v_mov_b32_e32 v91, v2
	v_mov_b32_e32 v92, v2
	v_mov_b32_e32 v93, v2
	v_mov_b32_e32 v94, v2
	v_mov_b32_e32 v95, v2
	v_mov_b32_e32 v96, v2
	v_mov_b32_e32 v97, v2
	v_mov_b32_e32 v106, v2
	v_mov_b32_e32 v107, v2
	v_mov_b32_e32 v108, v2
	v_mov_b32_e32 v109, v2
	v_mov_b32_e32 v110, v2
	v_mov_b32_e32 v111, v2
	v_mov_b32_e32 v112, v2
	v_mov_b32_e32 v113, v2
	v_mov_b32_e32 v122, v2
	v_mov_b32_e32 v123, v2
	v_mov_b32_e32 v124, v2
	v_mov_b32_e32 v125, v2
	v_mov_b32_e32 v126, v2
	v_mov_b32_e32 v127, v2
	v_mov_b32_e32 v128, v2
	v_mov_b32_e32 v129, v2
.LBB0_111:
	s_add_u32 s28, s26, 0xfffc0080
	s_addc_u32 s29, s27, -1
	s_add_i32 s57, 0, 0x10000
	s_cmp_eq_u32 s56, 12
	s_cselect_b32 s31, s19, s29
	s_cselect_b32 s30, s52, s28
	v_add_u32_e32 v150, s57, v1
	s_cselect_b32 s29, s17, s55
	s_cselect_b32 s28, s53, s54
	s_add_i32 s60, 0, 0x14000
.Lrot_u1:
	ds_read_b128 v[142:145], v150
	ds_read_b128 v[146:149], v150 offset:1024
	ds_read_b128 v[154:157], v150 offset:2048
	ds_read_b128 v[158:161], v150 offset:3072
	v_add_u32_e32 v150, s60, v1
	s_nop 0
	ds_read_b128 v[162:165], v150
	ds_read_b128 v[166:169], v150 offset:1024
	ds_read_b128 v[170:173], v150 offset:2048
	ds_read_b128 v[174:177], v150 offset:3072
	v_lshl_add_u64 v[150:151], s[26:27], 0, v[138:139]
	s_add_i32 m0, s43, 0xc000
	ds_read_b128 v[178:181], v152
	ds_read_b128 v[182:185], v152 offset:1024
	ds_read_b128 v[186:189], v152 offset:2048
	ds_read_b128 v[190:193], v152 offset:3072
	ds_read_b128 v[204:207], v152 offset:4096
	ds_read_b128 v[208:211], v152 offset:5120
	ds_read_b128 v[212:215], v152 offset:6144
	ds_read_b128 v[228:231], v152 offset:7168
	global_load_lds_dwordx4 v[150:151], off
	v_lshl_add_u64 v[150:151], s[26:27], 0, v[140:141]
	s_add_i32 m0, s43, 0xe000
	s_nop 0
	global_load_lds_dwordx4 v[150:151], off
	s_waitcnt vmcnt(8)
	s_waitcnt lgkmcnt(0)
	s_barrier
	s_setprio 1
	s_waitcnt lgkmcnt(0)
	v_mfma_f32_16x16x32_bf16 v[126:129], v[142:145], v[178:181], v[126:129]
	v_mfma_f32_16x16x32_bf16 v[122:125], v[154:157], v[178:181], v[122:125]
	v_mfma_f32_16x16x32_bf16 v[110:113], v[142:145], v[186:189], v[110:113]
	v_mfma_f32_16x16x32_bf16 v[106:109], v[154:157], v[186:189], v[106:109]
	v_mfma_f32_16x16x32_bf16 v[94:97], v[142:145], v[204:207], v[94:97]
	v_mfma_f32_16x16x32_bf16 v[90:93], v[154:157], v[204:207], v[90:93]
	v_mfma_f32_16x16x32_bf16 v[78:81], v[142:145], v[212:215], v[78:81]
	v_mfma_f32_16x16x32_bf16 v[74:77], v[154:157], v[212:215], v[74:77]
	v_mfma_f32_16x16x32_bf16 v[126:129], v[146:149], v[182:185], v[126:129]
	v_mfma_f32_16x16x32_bf16 v[122:125], v[158:161], v[182:185], v[122:125]
	v_mfma_f32_16x16x32_bf16 v[110:113], v[146:149], v[190:193], v[110:113]
	v_mfma_f32_16x16x32_bf16 v[106:109], v[158:161], v[190:193], v[106:109]
	v_mfma_f32_16x16x32_bf16 v[94:97], v[146:149], v[208:211], v[94:97]
	v_mfma_f32_16x16x32_bf16 v[90:93], v[158:161], v[208:211], v[90:93]
	v_mfma_f32_16x16x32_bf16 v[78:81], v[146:149], v[228:231], v[78:81]
	v_mfma_f32_16x16x32_bf16 v[74:77], v[158:161], v[228:231], v[74:77]
	v_mfma_f32_16x16x32_bf16 v[118:121], v[162:165], v[178:181], v[118:121]
	v_mfma_f32_16x16x32_bf16 v[114:117], v[170:173], v[178:181], v[114:117]
	v_mfma_f32_16x16x32_bf16 v[102:105], v[162:165], v[186:189], v[102:105]
	v_mfma_f32_16x16x32_bf16 v[98:101], v[170:173], v[186:189], v[98:101]
	v_mfma_f32_16x16x32_bf16 v[86:89], v[162:165], v[204:207], v[86:89]
	v_mfma_f32_16x16x32_bf16 v[82:85], v[170:173], v[204:207], v[82:85]
	v_mfma_f32_16x16x32_bf16 v[70:73], v[162:165], v[212:215], v[70:73]
	v_mfma_f32_16x16x32_bf16 v[66:69], v[170:173], v[212:215], v[66:69]
	v_mfma_f32_16x16x32_bf16 v[118:121], v[166:169], v[182:185], v[118:121]
	v_mfma_f32_16x16x32_bf16 v[114:117], v[174:177], v[182:185], v[114:117]
	v_mfma_f32_16x16x32_bf16 v[102:105], v[166:169], v[190:193], v[102:105]
	v_mfma_f32_16x16x32_bf16 v[98:101], v[174:177], v[190:193], v[98:101]
	v_mfma_f32_16x16x32_bf16 v[86:89], v[166:169], v[208:211], v[86:89]
	v_mfma_f32_16x16x32_bf16 v[82:85], v[174:177], v[208:211], v[82:85]
	v_mfma_f32_16x16x32_bf16 v[70:73], v[166:169], v[228:231], v[70:73]
	v_mfma_f32_16x16x32_bf16 v[66:69], v[174:177], v[228:231], v[66:69]
	s_setprio 0
	s_barrier
	s_add_i32 s57, s57, s42
	v_lshl_add_u64 v[150:151], s[28:29], 0, v[134:135]
	s_mov_b32 m0, s57
	ds_read_b128 v[178:181], v152 offset:16384
	ds_read_b128 v[182:185], v152 offset:17408
	ds_read_b128 v[186:189], v152 offset:18432
	ds_read_b128 v[190:193], v152 offset:19456
	ds_read_b128 v[204:207], v152 offset:20480
	ds_read_b128 v[208:211], v152 offset:21504
	ds_read_b128 v[212:215], v152 offset:22528
	ds_read_b128 v[228:231], v152 offset:23552
	global_load_lds_dwordx4 v[150:151], off
	s_add_i32 m0, s57, 0x2000
	s_add_u32 s58, s28, 0x40000
	v_lshl_add_u64 v[194:195], s[28:29], 0, v[130:131]
	s_addc_u32 s59, s29, 0
	s_add_i32 s57, s60, s42
	global_load_lds_dwordx4 v[194:195], off
	v_lshl_add_u64 v[216:217], s[58:59], 0, v[134:135]
	s_mov_b32 m0, s57
	v_lshl_add_u64 v[232:233], s[30:31], 0, v[132:133]
	global_load_lds_dwordx4 v[216:217], off
	v_lshl_add_u64 v[216:217], s[58:59], 0, v[130:131]
	s_add_i32 m0, s57, 0x2000
	s_nop 0
	global_load_lds_dwordx4 v[216:217], off
	v_lshl_add_u64 v[216:217], s[30:31], 0, v[136:137]
	s_mov_b32 m0, s43
	s_nop 0
	global_load_lds_dwordx4 v[216:217], off
	s_mov_b32 m0, s44
	s_nop 0
	global_load_lds_dwordx4 v[232:233], off
	s_waitcnt vmcnt(8)
	s_waitcnt lgkmcnt(0)
	s_barrier
	s_setprio 1
	s_waitcnt lgkmcnt(0)
	v_mfma_f32_16x16x32_bf16 v[62:65], v[142:145], v[178:181], v[62:65]
	v_mfma_f32_16x16x32_bf16 v[58:61], v[154:157], v[178:181], v[58:61]
	v_mfma_f32_16x16x32_bf16 v[46:49], v[142:145], v[186:189], v[46:49]
	v_mfma_f32_16x16x32_bf16 v[42:45], v[154:157], v[186:189], v[42:45]
	v_mfma_f32_16x16x32_bf16 v[30:33], v[142:145], v[204:207], v[30:33]
	v_mfma_f32_16x16x32_bf16 v[26:29], v[154:157], v[204:207], v[26:29]
	v_mfma_f32_16x16x32_bf16 v[14:17], v[142:145], v[212:215], v[14:17]
	v_mfma_f32_16x16x32_bf16 v[10:13], v[154:157], v[212:215], v[10:13]
	v_mfma_f32_16x16x32_bf16 v[62:65], v[146:149], v[182:185], v[62:65]
	v_mfma_f32_16x16x32_bf16 v[58:61], v[158:161], v[182:185], v[58:61]
	v_mfma_f32_16x16x32_bf16 v[46:49], v[146:149], v[190:193], v[46:49]
	v_mfma_f32_16x16x32_bf16 v[42:45], v[158:161], v[190:193], v[42:45]
	v_mfma_f32_16x16x32_bf16 v[30:33], v[146:149], v[208:211], v[30:33]
	v_mfma_f32_16x16x32_bf16 v[26:29], v[158:161], v[208:211], v[26:29]
	v_mfma_f32_16x16x32_bf16 v[14:17], v[146:149], v[228:231], v[14:17]
	v_mfma_f32_16x16x32_bf16 v[10:13], v[158:161], v[228:231], v[10:13]
	v_mfma_f32_16x16x32_bf16 v[54:57], v[162:165], v[178:181], v[54:57]
	v_mfma_f32_16x16x32_bf16 v[50:53], v[170:173], v[178:181], v[50:53]
	v_mfma_f32_16x16x32_bf16 v[38:41], v[162:165], v[186:189], v[38:41]
	v_mfma_f32_16x16x32_bf16 v[34:37], v[170:173], v[186:189], v[34:37]
	v_mfma_f32_16x16x32_bf16 v[22:25], v[162:165], v[204:207], v[22:25]
	v_mfma_f32_16x16x32_bf16 v[18:21], v[170:173], v[204:207], v[18:21]
	v_mfma_f32_16x16x32_bf16 v[6:9], v[162:165], v[212:215], v[6:9]
	v_mfma_f32_16x16x32_bf16 v[2:5], v[170:173], v[212:215], v[2:5]
	v_mfma_f32_16x16x32_bf16 v[54:57], v[166:169], v[182:185], v[54:57]
	v_mfma_f32_16x16x32_bf16 v[50:53], v[174:177], v[182:185], v[50:53]
	v_mfma_f32_16x16x32_bf16 v[38:41], v[166:169], v[190:193], v[38:41]
	v_mfma_f32_16x16x32_bf16 v[34:37], v[174:177], v[190:193], v[34:37]
	v_mfma_f32_16x16x32_bf16 v[22:25], v[166:169], v[208:211], v[22:25]
	v_mfma_f32_16x16x32_bf16 v[18:21], v[174:177], v[208:211], v[18:21]
	v_mfma_f32_16x16x32_bf16 v[6:9], v[166:169], v[228:231], v[6:9]
	v_mfma_f32_16x16x32_bf16 v[2:5], v[174:177], v[228:231], v[2:5]
	s_setprio 0
	s_barrier
	s_add_i32 s57, 0, 0x18000
	v_add_u32_e32 v153, s57, v1
	s_add_i32 s58, 0, 0x1c000
	ds_read_b128 v[142:145], v153
	ds_read_b128 v[146:149], v153 offset:1024
	ds_read_b128 v[154:157], v153 offset:2048
	ds_read_b128 v[158:161], v153 offset:3072
	v_add_u32_e32 v153, s58, v1
	ds_read_b128 v[162:165], v153
	ds_read_b128 v[166:169], v153 offset:1024
	ds_read_b128 v[170:173], v153 offset:2048
	ds_read_b128 v[174:177], v153 offset:3072
	s_add_u32 s30, s30, 0x40000
	s_addc_u32 s31, s31, 0
	s_mov_b32 m0, s45
	v_lshl_add_u64 v[234:235], s[30:31], 0, v[136:137]
	ds_read_b128 v[178:181], v152 offset:32768
	ds_read_b128 v[182:185], v152 offset:33792
	ds_read_b128 v[186:189], v152 offset:34816
	ds_read_b128 v[190:193], v152 offset:35840
	ds_read_b128 v[204:207], v152 offset:36864
	ds_read_b128 v[208:211], v152 offset:37888
	ds_read_b128 v[212:215], v152 offset:38912
	ds_read_b128 v[228:231], v152 offset:39936
	global_load_lds_dwordx4 v[234:235], off
	v_lshl_add_u64 v[234:235], s[30:31], 0, v[132:133]
	s_mov_b32 m0, s46
	s_nop 0
	global_load_lds_dwordx4 v[234:235], off
	s_waitcnt vmcnt(8)
	s_waitcnt lgkmcnt(0)
	s_barrier
	s_setprio 1
	s_waitcnt lgkmcnt(0)
	v_mfma_f32_16x16x32_bf16 v[126:129], v[142:145], v[178:181], v[126:129]
	v_mfma_f32_16x16x32_bf16 v[122:125], v[154:157], v[178:181], v[122:125]
	v_mfma_f32_16x16x32_bf16 v[110:113], v[142:145], v[186:189], v[110:113]
	v_mfma_f32_16x16x32_bf16 v[106:109], v[154:157], v[186:189], v[106:109]
	v_mfma_f32_16x16x32_bf16 v[94:97], v[142:145], v[204:207], v[94:97]
	v_mfma_f32_16x16x32_bf16 v[90:93], v[154:157], v[204:207], v[90:93]
	v_mfma_f32_16x16x32_bf16 v[78:81], v[142:145], v[212:215], v[78:81]
	v_mfma_f32_16x16x32_bf16 v[74:77], v[154:157], v[212:215], v[74:77]
	v_mfma_f32_16x16x32_bf16 v[126:129], v[146:149], v[182:185], v[126:129]
	v_mfma_f32_16x16x32_bf16 v[122:125], v[158:161], v[182:185], v[122:125]
	v_mfma_f32_16x16x32_bf16 v[110:113], v[146:149], v[190:193], v[110:113]
	v_mfma_f32_16x16x32_bf16 v[106:109], v[158:161], v[190:193], v[106:109]
	v_mfma_f32_16x16x32_bf16 v[94:97], v[146:149], v[208:211], v[94:97]
	v_mfma_f32_16x16x32_bf16 v[90:93], v[158:161], v[208:211], v[90:93]
	v_mfma_f32_16x16x32_bf16 v[78:81], v[146:149], v[228:231], v[78:81]
	v_mfma_f32_16x16x32_bf16 v[74:77], v[158:161], v[228:231], v[74:77]
	v_mfma_f32_16x16x32_bf16 v[118:121], v[162:165], v[178:181], v[118:121]
	v_mfma_f32_16x16x32_bf16 v[114:117], v[170:173], v[178:181], v[114:117]
	v_mfma_f32_16x16x32_bf16 v[102:105], v[162:165], v[186:189], v[102:105]
	v_mfma_f32_16x16x32_bf16 v[98:101], v[170:173], v[186:189], v[98:101]
	v_mfma_f32_16x16x32_bf16 v[86:89], v[162:165], v[204:207], v[86:89]
	v_mfma_f32_16x16x32_bf16 v[82:85], v[170:173], v[204:207], v[82:85]
	v_mfma_f32_16x16x32_bf16 v[70:73], v[162:165], v[212:215], v[70:73]
	v_mfma_f32_16x16x32_bf16 v[66:69], v[170:173], v[212:215], v[66:69]
	v_mfma_f32_16x16x32_bf16 v[118:121], v[166:169], v[182:185], v[118:121]
	v_mfma_f32_16x16x32_bf16 v[114:117], v[174:177], v[182:185], v[114:117]
	v_mfma_f32_16x16x32_bf16 v[102:105], v[166:169], v[190:193], v[102:105]
	v_mfma_f32_16x16x32_bf16 v[98:101], v[174:177], v[190:193], v[98:101]
	v_mfma_f32_16x16x32_bf16 v[86:89], v[166:169], v[208:211], v[86:89]
	v_mfma_f32_16x16x32_bf16 v[82:85], v[174:177], v[208:211], v[82:85]
	v_mfma_f32_16x16x32_bf16 v[70:73], v[166:169], v[228:231], v[70:73]
	v_mfma_f32_16x16x32_bf16 v[66:69], v[174:177], v[228:231], v[66:69]
	s_setprio 0
	s_barrier
	s_add_i32 s30, s57, s42
	v_lshl_add_u64 v[150:151], v[150:151], 0, s[94:95]
	s_mov_b32 m0, s30
	ds_read_b128 v[178:181], v152 offset:49152
	ds_read_b128 v[182:185], v152 offset:50176
	ds_read_b128 v[186:189], v152 offset:51200
	ds_read_b128 v[190:193], v152 offset:52224
	ds_read_b128 v[204:207], v152 offset:53248
	ds_read_b128 v[208:211], v152 offset:54272
	ds_read_b128 v[212:215], v152 offset:55296
	ds_read_b128 v[228:231], v152 offset:56320
	global_load_lds_dwordx4 v[150:151], off
	s_add_i32 m0, s30, 0x2000
	s_add_u32 s28, s28, 0x40080
	v_lshl_add_u64 v[150:151], v[194:195], 0, s[94:95]
	s_addc_u32 s29, s29, 0
	s_add_i32 s30, s58, s42
	global_load_lds_dwordx4 v[150:151], off
	v_lshl_add_u64 v[150:151], s[28:29], 0, v[134:135]
	s_mov_b32 m0, s30
	s_nop 0
	global_load_lds_dwordx4 v[150:151], off
	v_lshl_add_u64 v[150:151], s[28:29], 0, v[130:131]
	s_add_i32 m0, s30, 0x2000
	s_nop 0
	global_load_lds_dwordx4 v[150:151], off
	v_lshl_add_u64 v[150:151], v[216:217], 0, s[94:95]
	s_mov_b32 m0, s49
	s_nop 0
	global_load_lds_dwordx4 v[150:151], off
	v_lshl_add_u64 v[150:151], v[232:233], 0, s[94:95]
	s_mov_b32 m0, s50
	s_nop 0
	global_load_lds_dwordx4 v[150:151], off
	s_waitcnt vmcnt(8)
	s_waitcnt lgkmcnt(0)
	s_barrier
	s_setprio 1
	s_waitcnt lgkmcnt(0)
	v_mfma_f32_16x16x32_bf16 v[62:65], v[142:145], v[178:181], v[62:65]
	v_mfma_f32_16x16x32_bf16 v[58:61], v[154:157], v[178:181], v[58:61]
	v_mfma_f32_16x16x32_bf16 v[46:49], v[142:145], v[186:189], v[46:49]
	v_mfma_f32_16x16x32_bf16 v[42:45], v[154:157], v[186:189], v[42:45]
	v_mfma_f32_16x16x32_bf16 v[30:33], v[142:145], v[204:207], v[30:33]
	v_mfma_f32_16x16x32_bf16 v[26:29], v[154:157], v[204:207], v[26:29]
	v_mfma_f32_16x16x32_bf16 v[14:17], v[142:145], v[212:215], v[14:17]
	v_mfma_f32_16x16x32_bf16 v[10:13], v[154:157], v[212:215], v[10:13]
	v_mfma_f32_16x16x32_bf16 v[62:65], v[146:149], v[182:185], v[62:65]
	v_mfma_f32_16x16x32_bf16 v[58:61], v[158:161], v[182:185], v[58:61]
	v_mfma_f32_16x16x32_bf16 v[46:49], v[146:149], v[190:193], v[46:49]
	v_mfma_f32_16x16x32_bf16 v[42:45], v[158:161], v[190:193], v[42:45]
	v_mfma_f32_16x16x32_bf16 v[30:33], v[146:149], v[208:211], v[30:33]
	v_mfma_f32_16x16x32_bf16 v[26:29], v[158:161], v[208:211], v[26:29]
	v_mfma_f32_16x16x32_bf16 v[14:17], v[146:149], v[228:231], v[14:17]
	v_mfma_f32_16x16x32_bf16 v[10:13], v[158:161], v[228:231], v[10:13]
	v_mfma_f32_16x16x32_bf16 v[54:57], v[162:165], v[178:181], v[54:57]
	v_mfma_f32_16x16x32_bf16 v[50:53], v[170:173], v[178:181], v[50:53]
	v_mfma_f32_16x16x32_bf16 v[38:41], v[162:165], v[186:189], v[38:41]
	v_mfma_f32_16x16x32_bf16 v[34:37], v[170:173], v[186:189], v[34:37]
	v_mfma_f32_16x16x32_bf16 v[22:25], v[162:165], v[204:207], v[22:25]
	v_mfma_f32_16x16x32_bf16 v[18:21], v[170:173], v[204:207], v[18:21]
	v_mfma_f32_16x16x32_bf16 v[6:9], v[162:165], v[212:215], v[6:9]
	v_mfma_f32_16x16x32_bf16 v[2:5], v[170:173], v[212:215], v[2:5]
	v_mfma_f32_16x16x32_bf16 v[54:57], v[166:169], v[182:185], v[54:57]
	v_mfma_f32_16x16x32_bf16 v[50:53], v[174:177], v[182:185], v[50:53]
	v_mfma_f32_16x16x32_bf16 v[38:41], v[166:169], v[190:193], v[38:41]
	v_mfma_f32_16x16x32_bf16 v[34:37], v[174:177], v[190:193], v[34:37]
	v_mfma_f32_16x16x32_bf16 v[22:25], v[166:169], v[208:211], v[22:25]
	v_mfma_f32_16x16x32_bf16 v[18:21], v[174:177], v[208:211], v[18:21]
	v_mfma_f32_16x16x32_bf16 v[6:9], v[166:169], v[228:231], v[6:9]
	v_mfma_f32_16x16x32_bf16 v[2:5], v[174:177], v[228:231], v[2:5]
	s_setprio 0
	s_add_i32 s56, s56, 2
	s_add_u32 s26, s26, 0x100
	s_addc_u32 s27, s27, 0
	s_add_u32 s54, s54, 0x100
	s_addc_u32 s55, s55, 0
	s_add_u32 s28, s26, 0xfffc0080
	s_addc_u32 s29, s27, -1
	s_add_i32 s57, 0, 0x10000
	s_cmp_eq_u32 s56, 12
	s_cselect_b32 s31, s19, s29
	s_cselect_b32 s30, s52, s28
	v_add_u32_e32 v150, s57, v1
	s_cselect_b32 s29, s17, s55
	s_cselect_b32 s28, s53, s54
	s_add_i32 s60, 0, 0x14000
	s_cmp_gt_u32 s56, 13
	s_barrier
	s_cbranch_scc0 .Lrot_u1
	s_and_b64 vcc, exec, s[14:15]
	s_cbranch_vccz .LBB0_114
	s_barrier

.LBB0_1179:
	s_ashr_i32 s17, s16, 31
	s_lshl_b64 s[18:19], s[16:17], 19
	s_add_u32 s18, s34, s18
	s_addc_u32 s19, s35, s19
	s_and_b64 s[20:21], s[2:3], exec
	s_cselect_b32 s17, s19, s25
	s_cselect_b32 s50, s18, s24
	s_ashr_i32 s15, s14, 31
	s_lshl_b64 s[20:21], s[14:15], 19
	s_add_u32 s20, s36, s20
	s_addc_u32 s21, s37, s21
	s_and_b64 s[28:29], s[2:3], exec
	s_cselect_b32 s15, s21, s27
	s_cselect_b32 s51, s20, s26
	s_add_u32 s24, s24, 0x40080
	s_addc_u32 s25, s25, 0
	s_add_u32 s52, s26, 0x100
	v_mov_b32_e32 v2, 0
	s_addc_u32 s53, s27, 0
	s_mov_b32 s54, -2
	v_mov_b32_e32 v3, v2
	v_mov_b32_e32 v4, v2
	v_mov_b32_e32 v5, v2
	v_mov_b32_e32 v6, v2
	v_mov_b32_e32 v7, v2
	v_mov_b32_e32 v8, v2
	v_mov_b32_e32 v9, v2
	v_mov_b32_e32 v18, v2
	v_mov_b32_e32 v19, v2
	v_mov_b32_e32 v20, v2
	v_mov_b32_e32 v21, v2
	v_mov_b32_e32 v22, v2
	v_mov_b32_e32 v23, v2
	v_mov_b32_e32 v24, v2
	v_mov_b32_e32 v25, v2
	v_mov_b32_e32 v34, v2
	v_mov_b32_e32 v35, v2
	v_mov_b32_e32 v36, v2
	v_mov_b32_e32 v37, v2
	v_mov_b32_e32 v38, v2
	v_mov_b32_e32 v39, v2
	v_mov_b32_e32 v40, v2
	v_mov_b32_e32 v41, v2
	v_mov_b32_e32 v50, v2
	v_mov_b32_e32 v51, v2
	v_mov_b32_e32 v52, v2
	v_mov_b32_e32 v53, v2
	v_mov_b32_e32 v54, v2
	v_mov_b32_e32 v55, v2
	v_mov_b32_e32 v56, v2
	v_mov_b32_e32 v57, v2
	v_mov_b32_e32 v10, v2
	v_mov_b32_e32 v11, v2
	v_mov_b32_e32 v12, v2
	v_mov_b32_e32 v13, v2
	v_mov_b32_e32 v14, v2
	v_mov_b32_e32 v15, v2
	v_mov_b32_e32 v16, v2
	v_mov_b32_e32 v17, v2
	v_mov_b32_e32 v26, v2
	v_mov_b32_e32 v27, v2
	v_mov_b32_e32 v28, v2
	v_mov_b32_e32 v29, v2
	v_mov_b32_e32 v30, v2
	v_mov_b32_e32 v31, v2
	v_mov_b32_e32 v32, v2
	v_mov_b32_e32 v33, v2
	v_mov_b32_e32 v42, v2
	v_mov_b32_e32 v43, v2
	v_mov_b32_e32 v44, v2
	v_mov_b32_e32 v45, v2
	v_mov_b32_e32 v46, v2
	v_mov_b32_e32 v47, v2
	v_mov_b32_e32 v48, v2
	v_mov_b32_e32 v49, v2
	v_mov_b32_e32 v58, v2
	v_mov_b32_e32 v59, v2
	v_mov_b32_e32 v60, v2
	v_mov_b32_e32 v61, v2
	v_mov_b32_e32 v62, v2
	v_mov_b32_e32 v63, v2
	v_mov_b32_e32 v64, v2
	v_mov_b32_e32 v65, v2
	v_mov_b32_e32 v66, v2
	v_mov_b32_e32 v67, v2
	v_mov_b32_e32 v68, v2
	v_mov_b32_e32 v69, v2
	v_mov_b32_e32 v70, v2
	v_mov_b32_e32 v71, v2
	v_mov_b32_e32 v72, v2
	v_mov_b32_e32 v73, v2
	v_mov_b32_e32 v82, v2
	v_mov_b32_e32 v83, v2
	v_mov_b32_e32 v84, v2
	v_mov_b32_e32 v85, v2
	v_mov_b32_e32 v86, v2
	v_mov_b32_e32 v87, v2
	v_mov_b32_e32 v88, v2
	v_mov_b32_e32 v89, v2
	v_mov_b32_e32 v98, v2
	v_mov_b32_e32 v99, v2
	v_mov_b32_e32 v100, v2
	v_mov_b32_e32 v101, v2
	v_mov_b32_e32 v102, v2
	v_mov_b32_e32 v103, v2
	v_mov_b32_e32 v104, v2
	v_mov_b32_e32 v105, v2
	v_mov_b32_e32 v114, v2
	v_mov_b32_e32 v115, v2
	v_mov_b32_e32 v116, v2
	v_mov_b32_e32 v117, v2
	v_mov_b32_e32 v118, v2
	v_mov_b32_e32 v119, v2
	v_mov_b32_e32 v120, v2
	v_mov_b32_e32 v121, v2
	v_mov_b32_e32 v74, v2
	v_mov_b32_e32 v75, v2
	v_mov_b32_e32 v76, v2
	v_mov_b32_e32 v77, v2
	v_mov_b32_e32 v78, v2
	v_mov_b32_e32 v79, v2
	v_mov_b32_e32 v80, v2
	v_mov_b32_e32 v81, v2
	v_mov_b32_e32 v90, v2
	v_mov_b32_e32 v91, v2
	v_mov_b32_e32 v92, v2
	v_mov_b32_e32 v93, v2
	v_mov_b32_e32 v94, v2
	v_mov_b32_e32 v95, v2
	v_mov_b32_e32 v96, v2
	v_mov_b32_e32 v97, v2
	v_mov_b32_e32 v106, v2
	v_mov_b32_e32 v107, v2
	v_mov_b32_e32 v108, v2
	v_mov_b32_e32 v109, v2
	v_mov_b32_e32 v110, v2
	v_mov_b32_e32 v111, v2
	v_mov_b32_e32 v112, v2
	v_mov_b32_e32 v113, v2
	v_mov_b32_e32 v122, v2
	v_mov_b32_e32 v123, v2
	v_mov_b32_e32 v124, v2
	v_mov_b32_e32 v125, v2
	v_mov_b32_e32 v126, v2
	v_mov_b32_e32 v127, v2
	v_mov_b32_e32 v128, v2
	v_mov_b32_e32 v129, v2
	s_waitcnt vmcnt(0)
.LBB0_1180:
	s_add_u32 s26, s24, 0xfffc0080
	s_addc_u32 s27, s25, -1
	s_add_i32 s55, 0, 0x10000
	s_cmp_eq_u32 s54, 12
	s_cselect_b32 s29, s17, s27
	s_cselect_b32 s28, s50, s26
	v_add_u32_e32 v150, s55, v1
	s_cselect_b32 s27, s15, s53
	s_cselect_b32 s26, s51, s52
	s_add_i32 s58, 0, 0x14000
.Lrot_u2:
	ds_read_b128 v[142:145], v150
	ds_read_b128 v[146:149], v150 offset:1024
	ds_read_b128 v[154:157], v150 offset:2048
	ds_read_b128 v[158:161], v150 offset:3072
	v_add_u32_e32 v150, s58, v1
	ds_read_b128 v[162:165], v150
	ds_read_b128 v[166:169], v150 offset:1024
	ds_read_b128 v[170:173], v150 offset:2048
	ds_read_b128 v[174:177], v150 offset:3072
	v_lshl_add_u64 v[150:151], s[24:25], 0, v[138:139]
	s_add_i32 m0, s40, 0xc000
	ds_read_b128 v[178:181], v152
	ds_read_b128 v[182:185], v152 offset:1024
	ds_read_b128 v[186:189], v152 offset:2048
	ds_read_b128 v[190:193], v152 offset:3072
	ds_read_b128 v[204:207], v152 offset:4096
	ds_read_b128 v[208:211], v152 offset:5120
	ds_read_b128 v[212:215], v152 offset:6144
	ds_read_b128 v[228:231], v152 offset:7168
	global_load_lds_dwordx4 v[150:151], off
	v_lshl_add_u64 v[150:151], s[24:25], 0, v[140:141]
	s_add_i32 m0, s40, 0xe000
	s_nop 0
	global_load_lds_dwordx4 v[150:151], off
	s_waitcnt vmcnt(8)
	s_waitcnt lgkmcnt(0)
	s_barrier
	s_setprio 1
	s_waitcnt lgkmcnt(0)
	v_mfma_f32_16x16x32_bf16 v[126:129], v[142:145], v[178:181], v[126:129]
	v_mfma_f32_16x16x32_bf16 v[122:125], v[154:157], v[178:181], v[122:125]
	v_mfma_f32_16x16x32_bf16 v[110:113], v[142:145], v[186:189], v[110:113]
	v_mfma_f32_16x16x32_bf16 v[106:109], v[154:157], v[186:189], v[106:109]
	v_mfma_f32_16x16x32_bf16 v[94:97], v[142:145], v[204:207], v[94:97]
	v_mfma_f32_16x16x32_bf16 v[90:93], v[154:157], v[204:207], v[90:93]
	v_mfma_f32_16x16x32_bf16 v[78:81], v[142:145], v[212:215], v[78:81]
	v_mfma_f32_16x16x32_bf16 v[74:77], v[154:157], v[212:215], v[74:77]
	v_mfma_f32_16x16x32_bf16 v[126:129], v[146:149], v[182:185], v[126:129]
	v_mfma_f32_16x16x32_bf16 v[122:125], v[158:161], v[182:185], v[122:125]
	v_mfma_f32_16x16x32_bf16 v[110:113], v[146:149], v[190:193], v[110:113]
	v_mfma_f32_16x16x32_bf16 v[106:109], v[158:161], v[190:193], v[106:109]
	v_mfma_f32_16x16x32_bf16 v[94:97], v[146:149], v[208:211], v[94:97]
	v_mfma_f32_16x16x32_bf16 v[90:93], v[158:161], v[208:211], v[90:93]
	v_mfma_f32_16x16x32_bf16 v[78:81], v[146:149], v[228:231], v[78:81]
	v_mfma_f32_16x16x32_bf16 v[74:77], v[158:161], v[228:231], v[74:77]
	v_mfma_f32_16x16x32_bf16 v[118:121], v[162:165], v[178:181], v[118:121]
	v_mfma_f32_16x16x32_bf16 v[114:117], v[170:173], v[178:181], v[114:117]
	v_mfma_f32_16x16x32_bf16 v[102:105], v[162:165], v[186:189], v[102:105]
	v_mfma_f32_16x16x32_bf16 v[98:101], v[170:173], v[186:189], v[98:101]
	v_mfma_f32_16x16x32_bf16 v[86:89], v[162:165], v[204:207], v[86:89]
	v_mfma_f32_16x16x32_bf16 v[82:85], v[170:173], v[204:207], v[82:85]
	v_mfma_f32_16x16x32_bf16 v[70:73], v[162:165], v[212:215], v[70:73]
	v_mfma_f32_16x16x32_bf16 v[66:69], v[170:173], v[212:215], v[66:69]
	v_mfma_f32_16x16x32_bf16 v[118:121], v[166:169], v[182:185], v[118:121]
	v_mfma_f32_16x16x32_bf16 v[114:117], v[174:177], v[182:185], v[114:117]
	v_mfma_f32_16x16x32_bf16 v[102:105], v[166:169], v[190:193], v[102:105]
	v_mfma_f32_16x16x32_bf16 v[98:101], v[174:177], v[190:193], v[98:101]
	v_mfma_f32_16x16x32_bf16 v[86:89], v[166:169], v[208:211], v[86:89]
	v_mfma_f32_16x16x32_bf16 v[82:85], v[174:177], v[208:211], v[82:85]
	v_mfma_f32_16x16x32_bf16 v[70:73], v[166:169], v[228:231], v[70:73]
	v_mfma_f32_16x16x32_bf16 v[66:69], v[174:177], v[228:231], v[66:69]
	s_setprio 0
	s_barrier
	s_add_i32 s55, s55, s39
	v_lshl_add_u64 v[150:151], s[26:27], 0, v[134:135]
	s_mov_b32 m0, s55
	ds_read_b128 v[178:181], v152 offset:16384
	ds_read_b128 v[182:185], v152 offset:17408
	ds_read_b128 v[186:189], v152 offset:18432
	ds_read_b128 v[190:193], v152 offset:19456
	ds_read_b128 v[204:207], v152 offset:20480
	ds_read_b128 v[208:211], v152 offset:21504
	ds_read_b128 v[212:215], v152 offset:22528
	ds_read_b128 v[228:231], v152 offset:23552
	global_load_lds_dwordx4 v[150:151], off
	s_add_i32 m0, s55, 0x2000
	s_add_u32 s56, s26, 0x40000
	v_lshl_add_u64 v[194:195], s[26:27], 0, v[130:131]
	s_addc_u32 s57, s27, 0
	s_add_i32 s55, s58, s39
	global_load_lds_dwordx4 v[194:195], off
	v_lshl_add_u64 v[196:197], s[56:57], 0, v[134:135]
	s_mov_b32 m0, s55
	v_lshl_add_u64 v[198:199], s[28:29], 0, v[132:133]
	global_load_lds_dwordx4 v[196:197], off
	v_lshl_add_u64 v[196:197], s[56:57], 0, v[130:131]
	s_add_i32 m0, s55, 0x2000
	s_nop 0
	global_load_lds_dwordx4 v[196:197], off
	v_lshl_add_u64 v[196:197], s[28:29], 0, v[136:137]
	s_mov_b32 m0, s40
	s_nop 0
	global_load_lds_dwordx4 v[196:197], off
	s_mov_b32 m0, s41
	s_nop 0
	global_load_lds_dwordx4 v[198:199], off
	s_waitcnt vmcnt(8)
	s_waitcnt lgkmcnt(0)
	s_barrier
	s_setprio 1
	s_waitcnt lgkmcnt(0)
	v_mfma_f32_16x16x32_bf16 v[62:65], v[142:145], v[178:181], v[62:65]
	v_mfma_f32_16x16x32_bf16 v[58:61], v[154:157], v[178:181], v[58:61]
	v_mfma_f32_16x16x32_bf16 v[46:49], v[142:145], v[186:189], v[46:49]
	v_mfma_f32_16x16x32_bf16 v[42:45], v[154:157], v[186:189], v[42:45]
	v_mfma_f32_16x16x32_bf16 v[30:33], v[142:145], v[204:207], v[30:33]
	v_mfma_f32_16x16x32_bf16 v[26:29], v[154:157], v[204:207], v[26:29]
	v_mfma_f32_16x16x32_bf16 v[14:17], v[142:145], v[212:215], v[14:17]
	v_mfma_f32_16x16x32_bf16 v[10:13], v[154:157], v[212:215], v[10:13]
	v_mfma_f32_16x16x32_bf16 v[62:65], v[146:149], v[182:185], v[62:65]
	v_mfma_f32_16x16x32_bf16 v[58:61], v[158:161], v[182:185], v[58:61]
	v_mfma_f32_16x16x32_bf16 v[46:49], v[146:149], v[190:193], v[46:49]
	v_mfma_f32_16x16x32_bf16 v[42:45], v[158:161], v[190:193], v[42:45]
	v_mfma_f32_16x16x32_bf16 v[30:33], v[146:149], v[208:211], v[30:33]
	v_mfma_f32_16x16x32_bf16 v[26:29], v[158:161], v[208:211], v[26:29]
	v_mfma_f32_16x16x32_bf16 v[14:17], v[146:149], v[228:231], v[14:17]
	v_mfma_f32_16x16x32_bf16 v[10:13], v[158:161], v[228:231], v[10:13]
	v_mfma_f32_16x16x32_bf16 v[54:57], v[162:165], v[178:181], v[54:57]
	v_mfma_f32_16x16x32_bf16 v[50:53], v[170:173], v[178:181], v[50:53]
	v_mfma_f32_16x16x32_bf16 v[38:41], v[162:165], v[186:189], v[38:41]
	v_mfma_f32_16x16x32_bf16 v[34:37], v[170:173], v[186:189], v[34:37]
	v_mfma_f32_16x16x32_bf16 v[22:25], v[162:165], v[204:207], v[22:25]
	v_mfma_f32_16x16x32_bf16 v[18:21], v[170:173], v[204:207], v[18:21]
	v_mfma_f32_16x16x32_bf16 v[6:9], v[162:165], v[212:215], v[6:9]
	v_mfma_f32_16x16x32_bf16 v[2:5], v[170:173], v[212:215], v[2:5]
	v_mfma_f32_16x16x32_bf16 v[54:57], v[166:169], v[182:185], v[54:57]
	v_mfma_f32_16x16x32_bf16 v[50:53], v[174:177], v[182:185], v[50:53]
	v_mfma_f32_16x16x32_bf16 v[38:41], v[166:169], v[190:193], v[38:41]
	v_mfma_f32_16x16x32_bf16 v[34:37], v[174:177], v[190:193], v[34:37]
	v_mfma_f32_16x16x32_bf16 v[22:25], v[166:169], v[208:211], v[22:25]
	v_mfma_f32_16x16x32_bf16 v[18:21], v[174:177], v[208:211], v[18:21]
	v_mfma_f32_16x16x32_bf16 v[6:9], v[166:169], v[228:231], v[6:9]
	v_mfma_f32_16x16x32_bf16 v[2:5], v[174:177], v[228:231], v[2:5]
	s_setprio 0
	s_barrier
	s_add_i32 s55, 0, 0x18000
	v_add_u32_e32 v153, s55, v1
	s_add_i32 s56, 0, 0x1c000
	ds_read_b128 v[142:145], v153
	ds_read_b128 v[146:149], v153 offset:1024
	ds_read_b128 v[154:157], v153 offset:2048
	ds_read_b128 v[158:161], v153 offset:3072
	v_add_u32_e32 v153, s56, v1
	ds_read_b128 v[162:165], v153
	ds_read_b128 v[166:169], v153 offset:1024
	ds_read_b128 v[170:173], v153 offset:2048
	ds_read_b128 v[174:177], v153 offset:3072
	s_add_u32 s28, s28, 0x40000
	s_addc_u32 s29, s29, 0
	s_mov_b32 m0, s42
	v_lshl_add_u64 v[216:217], s[28:29], 0, v[136:137]
	ds_read_b128 v[178:181], v152 offset:32768
	ds_read_b128 v[182:185], v152 offset:33792
	ds_read_b128 v[186:189], v152 offset:34816
	ds_read_b128 v[190:193], v152 offset:35840
	ds_read_b128 v[204:207], v152 offset:36864
	ds_read_b128 v[208:211], v152 offset:37888
	ds_read_b128 v[212:215], v152 offset:38912
	ds_read_b128 v[228:231], v152 offset:39936
	global_load_lds_dwordx4 v[216:217], off
	v_lshl_add_u64 v[216:217], s[28:29], 0, v[132:133]
	s_mov_b32 m0, s43
	s_nop 0
	global_load_lds_dwordx4 v[216:217], off
	s_waitcnt vmcnt(8)
	s_waitcnt lgkmcnt(0)
	s_barrier
	s_setprio 1
	s_waitcnt lgkmcnt(0)
	v_mfma_f32_16x16x32_bf16 v[126:129], v[142:145], v[178:181], v[126:129]
	v_mfma_f32_16x16x32_bf16 v[122:125], v[154:157], v[178:181], v[122:125]
	v_mfma_f32_16x16x32_bf16 v[110:113], v[142:145], v[186:189], v[110:113]
	v_mfma_f32_16x16x32_bf16 v[106:109], v[154:157], v[186:189], v[106:109]
	v_mfma_f32_16x16x32_bf16 v[94:97], v[142:145], v[204:207], v[94:97]
	v_mfma_f32_16x16x32_bf16 v[90:93], v[154:157], v[204:207], v[90:93]
	v_mfma_f32_16x16x32_bf16 v[78:81], v[142:145], v[212:215], v[78:81]
	v_mfma_f32_16x16x32_bf16 v[74:77], v[154:157], v[212:215], v[74:77]
	v_mfma_f32_16x16x32_bf16 v[126:129], v[146:149], v[182:185], v[126:129]
	v_mfma_f32_16x16x32_bf16 v[122:125], v[158:161], v[182:185], v[122:125]
	v_mfma_f32_16x16x32_bf16 v[110:113], v[146:149], v[190:193], v[110:113]
	v_mfma_f32_16x16x32_bf16 v[106:109], v[158:161], v[190:193], v[106:109]
	v_mfma_f32_16x16x32_bf16 v[94:97], v[146:149], v[208:211], v[94:97]
	v_mfma_f32_16x16x32_bf16 v[90:93], v[158:161], v[208:211], v[90:93]
	v_mfma_f32_16x16x32_bf16 v[78:81], v[146:149], v[228:231], v[78:81]
	v_mfma_f32_16x16x32_bf16 v[74:77], v[158:161], v[228:231], v[74:77]
	v_mfma_f32_16x16x32_bf16 v[118:121], v[162:165], v[178:181], v[118:121]
	v_mfma_f32_16x16x32_bf16 v[114:117], v[170:173], v[178:181], v[114:117]
	v_mfma_f32_16x16x32_bf16 v[102:105], v[162:165], v[186:189], v[102:105]
	v_mfma_f32_16x16x32_bf16 v[98:101], v[170:173], v[186:189], v[98:101]
	v_mfma_f32_16x16x32_bf16 v[86:89], v[162:165], v[204:207], v[86:89]
	v_mfma_f32_16x16x32_bf16 v[82:85], v[170:173], v[204:207], v[82:85]
	v_mfma_f32_16x16x32_bf16 v[70:73], v[162:165], v[212:215], v[70:73]
	v_mfma_f32_16x16x32_bf16 v[66:69], v[170:173], v[212:215], v[66:69]
	v_mfma_f32_16x16x32_bf16 v[118:121], v[166:169], v[182:185], v[118:121]
	v_mfma_f32_16x16x32_bf16 v[114:117], v[174:177], v[182:185], v[114:117]
	v_mfma_f32_16x16x32_bf16 v[102:105], v[166:169], v[190:193], v[102:105]
	v_mfma_f32_16x16x32_bf16 v[98:101], v[174:177], v[190:193], v[98:101]
	v_mfma_f32_16x16x32_bf16 v[86:89], v[166:169], v[208:211], v[86:89]
	v_mfma_f32_16x16x32_bf16 v[82:85], v[174:177], v[208:211], v[82:85]
	v_mfma_f32_16x16x32_bf16 v[70:73], v[166:169], v[228:231], v[70:73]
	v_mfma_f32_16x16x32_bf16 v[66:69], v[174:177], v[228:231], v[66:69]
	s_setprio 0
	s_barrier
	s_add_i32 s28, s55, s39
	v_lshl_add_u64 v[150:151], v[150:151], 0, s[94:95]
	s_mov_b32 m0, s28
	ds_read_b128 v[178:181], v152 offset:49152
	ds_read_b128 v[182:185], v152 offset:50176
	ds_read_b128 v[186:189], v152 offset:51200
	ds_read_b128 v[190:193], v152 offset:52224
	ds_read_b128 v[204:207], v152 offset:53248
	ds_read_b128 v[208:211], v152 offset:54272
	ds_read_b128 v[212:215], v152 offset:55296
	ds_read_b128 v[228:231], v152 offset:56320
	global_load_lds_dwordx4 v[150:151], off
	s_add_i32 m0, s28, 0x2000
	s_add_u32 s26, s26, 0x40080
	v_lshl_add_u64 v[150:151], v[194:195], 0, s[94:95]
	s_addc_u32 s27, s27, 0
	s_add_i32 s28, s56, s39
	global_load_lds_dwordx4 v[150:151], off
	v_lshl_add_u64 v[150:151], s[26:27], 0, v[134:135]
	s_mov_b32 m0, s28
	s_nop 0
	global_load_lds_dwordx4 v[150:151], off
	v_lshl_add_u64 v[150:151], s[26:27], 0, v[130:131]
	s_add_i32 m0, s28, 0x2000
	s_nop 0
	global_load_lds_dwordx4 v[150:151], off
	v_lshl_add_u64 v[150:151], v[196:197], 0, s[94:95]
	s_mov_b32 m0, s47
	s_nop 0
	global_load_lds_dwordx4 v[150:151], off
	v_lshl_add_u64 v[150:151], v[198:199], 0, s[94:95]
	s_mov_b32 m0, s48
	s_nop 0
	global_load_lds_dwordx4 v[150:151], off
	s_waitcnt vmcnt(8)
	s_waitcnt lgkmcnt(0)
	s_barrier
	s_setprio 1
	s_waitcnt lgkmcnt(0)
	v_mfma_f32_16x16x32_bf16 v[62:65], v[142:145], v[178:181], v[62:65]
	v_mfma_f32_16x16x32_bf16 v[58:61], v[154:157], v[178:181], v[58:61]
	v_mfma_f32_16x16x32_bf16 v[46:49], v[142:145], v[186:189], v[46:49]
	v_mfma_f32_16x16x32_bf16 v[42:45], v[154:157], v[186:189], v[42:45]
	v_mfma_f32_16x16x32_bf16 v[30:33], v[142:145], v[204:207], v[30:33]
	v_mfma_f32_16x16x32_bf16 v[26:29], v[154:157], v[204:207], v[26:29]
	v_mfma_f32_16x16x32_bf16 v[14:17], v[142:145], v[212:215], v[14:17]
	v_mfma_f32_16x16x32_bf16 v[10:13], v[154:157], v[212:215], v[10:13]
	v_mfma_f32_16x16x32_bf16 v[62:65], v[146:149], v[182:185], v[62:65]
	v_mfma_f32_16x16x32_bf16 v[58:61], v[158:161], v[182:185], v[58:61]
	v_mfma_f32_16x16x32_bf16 v[46:49], v[146:149], v[190:193], v[46:49]
	v_mfma_f32_16x16x32_bf16 v[42:45], v[158:161], v[190:193], v[42:45]
	v_mfma_f32_16x16x32_bf16 v[30:33], v[146:149], v[208:211], v[30:33]
	v_mfma_f32_16x16x32_bf16 v[26:29], v[158:161], v[208:211], v[26:29]
	v_mfma_f32_16x16x32_bf16 v[14:17], v[146:149], v[228:231], v[14:17]
	v_mfma_f32_16x16x32_bf16 v[10:13], v[158:161], v[228:231], v[10:13]
	v_mfma_f32_16x16x32_bf16 v[54:57], v[162:165], v[178:181], v[54:57]
	v_mfma_f32_16x16x32_bf16 v[50:53], v[170:173], v[178:181], v[50:53]
	v_mfma_f32_16x16x32_bf16 v[38:41], v[162:165], v[186:189], v[38:41]
	v_mfma_f32_16x16x32_bf16 v[34:37], v[170:173], v[186:189], v[34:37]
	v_mfma_f32_16x16x32_bf16 v[22:25], v[162:165], v[204:207], v[22:25]
	v_mfma_f32_16x16x32_bf16 v[18:21], v[170:173], v[204:207], v[18:21]
	v_mfma_f32_16x16x32_bf16 v[6:9], v[162:165], v[212:215], v[6:9]
	v_mfma_f32_16x16x32_bf16 v[2:5], v[170:173], v[212:215], v[2:5]
	v_mfma_f32_16x16x32_bf16 v[54:57], v[166:169], v[182:185], v[54:57]
	v_mfma_f32_16x16x32_bf16 v[50:53], v[174:177], v[182:185], v[50:53]
	v_mfma_f32_16x16x32_bf16 v[38:41], v[166:169], v[190:193], v[38:41]
	v_mfma_f32_16x16x32_bf16 v[34:37], v[174:177], v[190:193], v[34:37]
	v_mfma_f32_16x16x32_bf16 v[22:25], v[166:169], v[208:211], v[22:25]
	v_mfma_f32_16x16x32_bf16 v[18:21], v[174:177], v[208:211], v[18:21]
	v_mfma_f32_16x16x32_bf16 v[6:9], v[166:169], v[228:231], v[6:9]
	v_mfma_f32_16x16x32_bf16 v[2:5], v[174:177], v[228:231], v[2:5]
	s_setprio 0
	s_add_i32 s54, s54, 2
	s_add_u32 s24, s24, 0x100
	s_addc_u32 s25, s25, 0
	s_add_u32 s52, s52, 0x100
	s_addc_u32 s53, s53, 0
	s_add_u32 s26, s24, 0xfffc0080
	s_addc_u32 s27, s25, -1
	s_add_i32 s55, 0, 0x10000
	s_cmp_eq_u32 s54, 12
	s_cselect_b32 s29, s17, s27
	s_cselect_b32 s28, s50, s26
	v_add_u32_e32 v150, s55, v1
	s_cselect_b32 s27, s15, s53
	s_cselect_b32 s26, s51, s52
	s_add_i32 s58, 0, 0x14000
	s_cmp_gt_u32 s54, 13
	s_barrier
	s_cbranch_scc0 .Lrot_u2
	s_and_b64 vcc, exec, s[12:13]
	s_cbranch_vccz .LBB0_1183
	s_barrier
